# P11 fixup_rows hand-written: all 96 loads of a thread in flight at once instead of six serialized column passes
# speedup vs baseline: 1.0126x; 1.0038x over previous
.LBB0_1271:
	s_ashr_i32 s4, s8, 3
	s_add_i32 s4, s10, s4
	s_ashr_i32 s5, s4, 31
	s_lshr_b32 s5, s5, 27
	s_add_i32 s5, s4, s5
	s_ashr_i32 s8, s5, 5
	s_and_b32 s5, s5, 0xffe0
	s_sub_i32 s4, s4, s5
	s_lshl_b32 s5, s8, 3
	s_bfe_i32 s8, s4, 0x80000
	s_bfe_u32 s8, s8, 0x3000c
	s_add_i32 s8, s4, s8
	s_and_b32 s8, s8, 0xf8
	s_sub_i32 s4, s4, s8
	s_sext_i32_i8 s4, s4
	s_add_i32 s8, s5, s4
	s_waitcnt lgkmcnt(0)
	s_mul_i32 s4, s8, 0xb000
	s_mul_hi_i32 s5, s8, 0xb000
	s_add_u32 s12, s2, s4
	s_addc_u32 s13, s3, s5
	s_add_u32 s14, s12, 0x1600
	s_addc_u32 s15, s13, 0
	s_add_u32 s16, s12, 0x2c00
	s_addc_u32 s17, s13, 0
	s_add_u32 s18, s12, 0x4200
	s_addc_u32 s19, s13, 0
	s_add_u32 s20, s12, 0x5800
	s_addc_u32 s21, s13, 0
	s_add_u32 s22, s12, 0x6e00
	s_addc_u32 s23, s13, 0
	s_add_u32 s24, s12, 0x8400
	s_addc_u32 s25, s13, 0
	s_add_u32 s26, s12, 0x9a00
	s_addc_u32 s27, s13, 0
	s_mul_i32 s4, s8, 0x160000
	s_mul_hi_i32 s5, s8, 0x160000
	s_add_u32 s28, s2, s4
	s_addc_u32 s29, s3, s5
	s_add_u32 s28, s28, 0x4900000
	s_addc_u32 s29, s29, 0
	s_add_u32 s30, s28, 0x1600
	s_addc_u32 s31, s29, 0
	s_load_dwordx4 s[48:51], s[0:1], 0xb8
	s_and_b32 s52, s8, 31
	s_cmp_eq_u32 s52, 0
	s_cselect_b32 s52, 0, -1
	v_lshlrev_b32_e32 v112, 0x1, v192
	v_add_u32_e32 v113, 0x1000, v112
	v_lshlrev_b32_e32 v114, 0x2, v192
	v_add_u32_e32 v115, 0x1000, v114
	v_add_u32_e32 v116, 0x2000, v114
	s_waitcnt lgkmcnt(0)
	s_add_u32 s54, s50, 0x2c00
	s_addc_u32 s55, s51, 0
	s_add_u32 s56, s48, 0x5800
	s_addc_u32 s57, s49, 0
	s_add_u32 s58, s48, 0xb000
	s_addc_u32 s59, s49, 0
	s_add_u32 s60, s48, 0x2c00
	s_addc_u32 s61, s49, 0
	s_add_u32 s62, s48, 0x8400
	s_addc_u32 s63, s49, 0
	s_add_u32 s64, s48, 0xdc00
	s_addc_u32 s65, s49, 0
	v_readfirstlane_b32 s53, v192
	global_load_ushort v0, v112, s[12:13]
	global_load_ushort v4, v112, s[14:15]
	global_load_ushort v1, v112, s[16:17]
	global_load_ushort v5, v112, s[18:19]
	global_load_ushort v2, v112, s[20:21]
	global_load_ushort v6, v112, s[22:23]
	global_load_ushort v3, v112, s[24:25]
	global_load_ushort v7, v112, s[26:27]
	global_load_dword v8, v114, s[50:51]
	global_load_dword v9, v114, s[54:55]
	global_load_dword v10, v114, s[48:49]
	global_load_dword v11, v114, s[56:57]
	global_load_dword v12, v114, s[58:59]
	global_load_dword v13, v114, s[60:61]
	global_load_dword v14, v114, s[62:63]
	global_load_dword v15, v114, s[64:65]
	global_load_ushort v16, v112, s[12:13] offset:1024
	global_load_ushort v20, v112, s[14:15] offset:1024
	global_load_ushort v17, v112, s[16:17] offset:1024
	global_load_ushort v21, v112, s[18:19] offset:1024
	global_load_ushort v18, v112, s[20:21] offset:1024
	global_load_ushort v22, v112, s[22:23] offset:1024
	global_load_ushort v19, v112, s[24:25] offset:1024
	global_load_ushort v23, v112, s[26:27] offset:1024
	global_load_dword v24, v114, s[50:51] offset:2048
	global_load_dword v25, v114, s[54:55] offset:2048
	global_load_dword v26, v114, s[48:49] offset:2048
	global_load_dword v27, v114, s[56:57] offset:2048
	global_load_dword v28, v114, s[58:59] offset:2048
	global_load_dword v29, v114, s[60:61] offset:2048
	global_load_dword v30, v114, s[62:63] offset:2048
	global_load_dword v31, v114, s[64:65] offset:2048
	global_load_ushort v32, v112, s[12:13] offset:2048
	global_load_ushort v36, v112, s[14:15] offset:2048
	global_load_ushort v33, v112, s[16:17] offset:2048
	global_load_ushort v37, v112, s[18:19] offset:2048
	global_load_ushort v34, v112, s[20:21] offset:2048
	global_load_ushort v38, v112, s[22:23] offset:2048
	global_load_ushort v35, v112, s[24:25] offset:2048
	global_load_ushort v39, v112, s[26:27] offset:2048
	global_load_dword v40, v115, s[50:51]
	global_load_dword v41, v115, s[54:55]
	global_load_dword v42, v115, s[48:49]
	global_load_dword v43, v115, s[56:57]
	global_load_dword v44, v115, s[58:59]
	global_load_dword v45, v115, s[60:61]
	global_load_dword v46, v115, s[62:63]
	global_load_dword v47, v115, s[64:65]
	global_load_ushort v48, v112, s[12:13] offset:3072
	global_load_ushort v52, v112, s[14:15] offset:3072
	global_load_ushort v49, v112, s[16:17] offset:3072
	global_load_ushort v53, v112, s[18:19] offset:3072
	global_load_ushort v50, v112, s[20:21] offset:3072
	global_load_ushort v54, v112, s[22:23] offset:3072
	global_load_ushort v51, v112, s[24:25] offset:3072
	global_load_ushort v55, v112, s[26:27] offset:3072
	global_load_dword v56, v115, s[50:51] offset:2048
	global_load_dword v57, v115, s[54:55] offset:2048
	global_load_dword v58, v115, s[48:49] offset:2048
	global_load_dword v59, v115, s[56:57] offset:2048
	global_load_dword v60, v115, s[58:59] offset:2048
	global_load_dword v61, v115, s[60:61] offset:2048
	global_load_dword v62, v115, s[62:63] offset:2048
	global_load_dword v63, v115, s[64:65] offset:2048
	global_load_ushort v64, v113, s[12:13]
	global_load_ushort v68, v113, s[14:15]
	global_load_ushort v65, v113, s[16:17]
	global_load_ushort v69, v113, s[18:19]
	global_load_ushort v66, v113, s[20:21]
	global_load_ushort v70, v113, s[22:23]
	global_load_ushort v67, v113, s[24:25]
	global_load_ushort v71, v113, s[26:27]
	global_load_dword v72, v116, s[50:51]
	global_load_dword v73, v116, s[54:55]
	global_load_dword v74, v116, s[48:49]
	global_load_dword v75, v116, s[56:57]
	global_load_dword v76, v116, s[58:59]
	global_load_dword v77, v116, s[60:61]
	global_load_dword v78, v116, s[62:63]
	global_load_dword v79, v116, s[64:65]
	s_cmp_gt_u32 s53, 255
	s_cbranch_scc1 .Lfix11_no5a
	global_load_ushort v80, v113, s[12:13] offset:1024
	global_load_ushort v84, v113, s[14:15] offset:1024
	global_load_ushort v81, v113, s[16:17] offset:1024
	global_load_ushort v85, v113, s[18:19] offset:1024
	global_load_ushort v82, v113, s[20:21] offset:1024
	global_load_ushort v86, v113, s[22:23] offset:1024
	global_load_ushort v83, v113, s[24:25] offset:1024
	global_load_ushort v87, v113, s[26:27] offset:1024
	global_load_dword v88, v116, s[50:51] offset:2048
	global_load_dword v89, v116, s[54:55] offset:2048
	global_load_dword v90, v116, s[48:49] offset:2048
	global_load_dword v91, v116, s[56:57] offset:2048
	global_load_dword v92, v116, s[58:59] offset:2048
	global_load_dword v93, v116, s[60:61] offset:2048
	global_load_dword v94, v116, s[62:63] offset:2048
	global_load_dword v95, v116, s[64:65] offset:2048
.Lfix11_no5a:
	s_waitcnt vmcnt(0)
	v_lshlrev_b32_e32 v0, 0x10, v0
	v_lshlrev_b32_e32 v4, 0x10, v4
	v_lshlrev_b32_e32 v1, 0x10, v1
	v_lshlrev_b32_e32 v5, 0x10, v5
	v_lshlrev_b32_e32 v2, 0x10, v2
	v_lshlrev_b32_e32 v6, 0x10, v6
	v_lshlrev_b32_e32 v3, 0x10, v3
	v_lshlrev_b32_e32 v7, 0x10, v7
	v_and_b32_e32 v0, s52, v0
	v_and_b32_e32 v4, s52, v4
	v_and_b32_e32 v1, s52, v1
	v_and_b32_e32 v5, s52, v5
	v_fma_f32 v96, v10, v0, v8
	v_fma_f32 v97, v13, v4, v9
	v_fma_f32 v96, v11, v1, v96
	v_fma_f32 v97, v14, v5, v97
	v_fma_f32 v96, v12, v2, v96
	v_fma_f32 v97, v15, v6, v97
	v_fma_f32 v100, v10, v1, v8
	v_fma_f32 v101, v13, v5, v9
	v_fma_f32 v100, v11, v2, v100
	v_fma_f32 v101, v14, v6, v101
	v_fma_f32 v100, v12, v3, v100
	v_fma_f32 v101, v15, v7, v101
	v_mul_f32_e32 v98, 0x3d372713, v96
	v_mul_f32_e32 v102, 0x3d372713, v100
	v_mul_f32_e32 v98, v96, v98
	v_mul_f32_e32 v102, v100, v102
	v_fma_f32 v98, v96, v98, v96
	v_fma_f32 v102, v100, v102, v100
	v_mul_f32_e32 v98, 0x3f4c422a, v98
	v_mul_f32_e32 v102, 0x3f4c422a, v102
	v_add_f32_e32 v98, v98, v98
	v_add_f32_e32 v102, v102, v102
	v_mul_f32_e32 v98, 0xbfb8aa3b, v98
	v_mul_f32_e32 v102, 0xbfb8aa3b, v102
	v_exp_f32_e32 v98, v98
	v_exp_f32_e32 v102, v102
	s_nop 0
	v_add_f32_e32 v98, 1.0, v98
	v_add_f32_e32 v102, 1.0, v102
	v_rcp_f32_e32 v98, v98
	v_rcp_f32_e32 v102, v102
	s_nop 0
	v_mul_f32_e32 v96, v96, v98
	v_mul_f32_e32 v100, v100, v102
	v_mul_f32_e32 v96, v96, v97
	v_mul_f32_e32 v100, v100, v101
	v_cvt_pk_bf16_f32 v96, v96, v96
	v_cvt_pk_bf16_f32 v100, v100, v100
	global_store_short v112, v96, s[28:29]
	global_store_short v112, v100, s[30:31]
	v_lshlrev_b32_e32 v16, 0x10, v16
	v_lshlrev_b32_e32 v20, 0x10, v20
	v_lshlrev_b32_e32 v17, 0x10, v17
	v_lshlrev_b32_e32 v21, 0x10, v21
	v_lshlrev_b32_e32 v18, 0x10, v18
	v_lshlrev_b32_e32 v22, 0x10, v22
	v_lshlrev_b32_e32 v19, 0x10, v19
	v_lshlrev_b32_e32 v23, 0x10, v23
	v_and_b32_e32 v16, s52, v16
	v_and_b32_e32 v20, s52, v20
	v_and_b32_e32 v17, s52, v17
	v_and_b32_e32 v21, s52, v21
	v_fma_f32 v96, v26, v16, v24
	v_fma_f32 v97, v29, v20, v25
	v_fma_f32 v96, v27, v17, v96
	v_fma_f32 v97, v30, v21, v97
	v_fma_f32 v96, v28, v18, v96
	v_fma_f32 v97, v31, v22, v97
	v_fma_f32 v100, v26, v17, v24
	v_fma_f32 v101, v29, v21, v25
	v_fma_f32 v100, v27, v18, v100
	v_fma_f32 v101, v30, v22, v101
	v_fma_f32 v100, v28, v19, v100
	v_fma_f32 v101, v31, v23, v101
	v_mul_f32_e32 v98, 0x3d372713, v96
	v_mul_f32_e32 v102, 0x3d372713, v100
	v_mul_f32_e32 v98, v96, v98
	v_mul_f32_e32 v102, v100, v102
	v_fma_f32 v98, v96, v98, v96
	v_fma_f32 v102, v100, v102, v100
	v_mul_f32_e32 v98, 0x3f4c422a, v98
	v_mul_f32_e32 v102, 0x3f4c422a, v102
	v_add_f32_e32 v98, v98, v98
	v_add_f32_e32 v102, v102, v102
	v_mul_f32_e32 v98, 0xbfb8aa3b, v98
	v_mul_f32_e32 v102, 0xbfb8aa3b, v102
	v_exp_f32_e32 v98, v98
	v_exp_f32_e32 v102, v102
	s_nop 0
	v_add_f32_e32 v98, 1.0, v98
	v_add_f32_e32 v102, 1.0, v102
	v_rcp_f32_e32 v98, v98
	v_rcp_f32_e32 v102, v102
	s_nop 0
	v_mul_f32_e32 v96, v96, v98
	v_mul_f32_e32 v100, v100, v102
	v_mul_f32_e32 v96, v96, v97
	v_mul_f32_e32 v100, v100, v101
	v_cvt_pk_bf16_f32 v96, v96, v96
	v_cvt_pk_bf16_f32 v100, v100, v100
	global_store_short v112, v96, s[28:29] offset:1024
	global_store_short v112, v100, s[30:31] offset:1024
	v_lshlrev_b32_e32 v32, 0x10, v32
	v_lshlrev_b32_e32 v36, 0x10, v36
	v_lshlrev_b32_e32 v33, 0x10, v33
	v_lshlrev_b32_e32 v37, 0x10, v37
	v_lshlrev_b32_e32 v34, 0x10, v34
	v_lshlrev_b32_e32 v38, 0x10, v38
	v_lshlrev_b32_e32 v35, 0x10, v35
	v_lshlrev_b32_e32 v39, 0x10, v39
	v_and_b32_e32 v32, s52, v32
	v_and_b32_e32 v36, s52, v36
	v_and_b32_e32 v33, s52, v33
	v_and_b32_e32 v37, s52, v37
	v_fma_f32 v96, v42, v32, v40
	v_fma_f32 v97, v45, v36, v41
	v_fma_f32 v96, v43, v33, v96
	v_fma_f32 v97, v46, v37, v97
	v_fma_f32 v96, v44, v34, v96
	v_fma_f32 v97, v47, v38, v97
	v_fma_f32 v100, v42, v33, v40
	v_fma_f32 v101, v45, v37, v41
	v_fma_f32 v100, v43, v34, v100
	v_fma_f32 v101, v46, v38, v101
	v_fma_f32 v100, v44, v35, v100
	v_fma_f32 v101, v47, v39, v101
	v_mul_f32_e32 v98, 0x3d372713, v96
	v_mul_f32_e32 v102, 0x3d372713, v100
	v_mul_f32_e32 v98, v96, v98
	v_mul_f32_e32 v102, v100, v102
	v_fma_f32 v98, v96, v98, v96
	v_fma_f32 v102, v100, v102, v100
	v_mul_f32_e32 v98, 0x3f4c422a, v98
	v_mul_f32_e32 v102, 0x3f4c422a, v102
	v_add_f32_e32 v98, v98, v98
	v_add_f32_e32 v102, v102, v102
	v_mul_f32_e32 v98, 0xbfb8aa3b, v98
	v_mul_f32_e32 v102, 0xbfb8aa3b, v102
	v_exp_f32_e32 v98, v98
	v_exp_f32_e32 v102, v102
	s_nop 0
	v_add_f32_e32 v98, 1.0, v98
	v_add_f32_e32 v102, 1.0, v102
	v_rcp_f32_e32 v98, v98
	v_rcp_f32_e32 v102, v102
	s_nop 0
	v_mul_f32_e32 v96, v96, v98
	v_mul_f32_e32 v100, v100, v102
	v_mul_f32_e32 v96, v96, v97
	v_mul_f32_e32 v100, v100, v101
	v_cvt_pk_bf16_f32 v96, v96, v96
	v_cvt_pk_bf16_f32 v100, v100, v100
	global_store_short v112, v96, s[28:29] offset:2048
	global_store_short v112, v100, s[30:31] offset:2048
	v_lshlrev_b32_e32 v48, 0x10, v48
	v_lshlrev_b32_e32 v52, 0x10, v52
	v_lshlrev_b32_e32 v49, 0x10, v49
	v_lshlrev_b32_e32 v53, 0x10, v53
	v_lshlrev_b32_e32 v50, 0x10, v50
	v_lshlrev_b32_e32 v54, 0x10, v54
	v_lshlrev_b32_e32 v51, 0x10, v51
	v_lshlrev_b32_e32 v55, 0x10, v55
	v_and_b32_e32 v48, s52, v48
	v_and_b32_e32 v52, s52, v52
	v_and_b32_e32 v49, s52, v49
	v_and_b32_e32 v53, s52, v53
	v_fma_f32 v96, v58, v48, v56
	v_fma_f32 v97, v61, v52, v57
	v_fma_f32 v96, v59, v49, v96
	v_fma_f32 v97, v62, v53, v97
	v_fma_f32 v96, v60, v50, v96
	v_fma_f32 v97, v63, v54, v97
	v_fma_f32 v100, v58, v49, v56
	v_fma_f32 v101, v61, v53, v57
	v_fma_f32 v100, v59, v50, v100
	v_fma_f32 v101, v62, v54, v101
	v_fma_f32 v100, v60, v51, v100
	v_fma_f32 v101, v63, v55, v101
	v_mul_f32_e32 v98, 0x3d372713, v96
	v_mul_f32_e32 v102, 0x3d372713, v100
	v_mul_f32_e32 v98, v96, v98
	v_mul_f32_e32 v102, v100, v102
	v_fma_f32 v98, v96, v98, v96
	v_fma_f32 v102, v100, v102, v100
	v_mul_f32_e32 v98, 0x3f4c422a, v98
	v_mul_f32_e32 v102, 0x3f4c422a, v102
	v_add_f32_e32 v98, v98, v98
	v_add_f32_e32 v102, v102, v102
	v_mul_f32_e32 v98, 0xbfb8aa3b, v98
	v_mul_f32_e32 v102, 0xbfb8aa3b, v102
	v_exp_f32_e32 v98, v98
	v_exp_f32_e32 v102, v102
	s_nop 0
	v_add_f32_e32 v98, 1.0, v98
	v_add_f32_e32 v102, 1.0, v102
	v_rcp_f32_e32 v98, v98
	v_rcp_f32_e32 v102, v102
	s_nop 0
	v_mul_f32_e32 v96, v96, v98
	v_mul_f32_e32 v100, v100, v102
	v_mul_f32_e32 v96, v96, v97
	v_mul_f32_e32 v100, v100, v101
	v_cvt_pk_bf16_f32 v96, v96, v96
	v_cvt_pk_bf16_f32 v100, v100, v100
	global_store_short v112, v96, s[28:29] offset:3072
	global_store_short v112, v100, s[30:31] offset:3072
	v_lshlrev_b32_e32 v64, 0x10, v64
	v_lshlrev_b32_e32 v68, 0x10, v68
	v_lshlrev_b32_e32 v65, 0x10, v65
	v_lshlrev_b32_e32 v69, 0x10, v69
	v_lshlrev_b32_e32 v66, 0x10, v66
	v_lshlrev_b32_e32 v70, 0x10, v70
	v_lshlrev_b32_e32 v67, 0x10, v67
	v_lshlrev_b32_e32 v71, 0x10, v71
	v_and_b32_e32 v64, s52, v64
	v_and_b32_e32 v68, s52, v68
	v_and_b32_e32 v65, s52, v65
	v_and_b32_e32 v69, s52, v69
	v_fma_f32 v96, v74, v64, v72
	v_fma_f32 v97, v77, v68, v73
	v_fma_f32 v96, v75, v65, v96
	v_fma_f32 v97, v78, v69, v97
	v_fma_f32 v96, v76, v66, v96
	v_fma_f32 v97, v79, v70, v97
	v_fma_f32 v100, v74, v65, v72
	v_fma_f32 v101, v77, v69, v73
	v_fma_f32 v100, v75, v66, v100
	v_fma_f32 v101, v78, v70, v101
	v_fma_f32 v100, v76, v67, v100
	v_fma_f32 v101, v79, v71, v101
	v_mul_f32_e32 v98, 0x3d372713, v96
	v_mul_f32_e32 v102, 0x3d372713, v100
	v_mul_f32_e32 v98, v96, v98
	v_mul_f32_e32 v102, v100, v102
	v_fma_f32 v98, v96, v98, v96
	v_fma_f32 v102, v100, v102, v100
	v_mul_f32_e32 v98, 0x3f4c422a, v98
	v_mul_f32_e32 v102, 0x3f4c422a, v102
	v_add_f32_e32 v98, v98, v98
	v_add_f32_e32 v102, v102, v102
	v_mul_f32_e32 v98, 0xbfb8aa3b, v98
	v_mul_f32_e32 v102, 0xbfb8aa3b, v102
	v_exp_f32_e32 v98, v98
	v_exp_f32_e32 v102, v102
	s_nop 0
	v_add_f32_e32 v98, 1.0, v98
	v_add_f32_e32 v102, 1.0, v102
	v_rcp_f32_e32 v98, v98
	v_rcp_f32_e32 v102, v102
	s_nop 0
	v_mul_f32_e32 v96, v96, v98
	v_mul_f32_e32 v100, v100, v102
	v_mul_f32_e32 v96, v96, v97
	v_mul_f32_e32 v100, v100, v101
	v_cvt_pk_bf16_f32 v96, v96, v96
	v_cvt_pk_bf16_f32 v100, v100, v100
	global_store_short v113, v96, s[28:29]
	global_store_short v113, v100, s[30:31]
	s_cmp_gt_u32 s53, 255
	s_cbranch_scc1 .Lfix11_no5b
	v_lshlrev_b32_e32 v80, 0x10, v80
	v_lshlrev_b32_e32 v84, 0x10, v84
	v_lshlrev_b32_e32 v81, 0x10, v81
	v_lshlrev_b32_e32 v85, 0x10, v85
	v_lshlrev_b32_e32 v82, 0x10, v82
	v_lshlrev_b32_e32 v86, 0x10, v86
	v_lshlrev_b32_e32 v83, 0x10, v83
	v_lshlrev_b32_e32 v87, 0x10, v87
	v_and_b32_e32 v80, s52, v80
	v_and_b32_e32 v84, s52, v84
	v_and_b32_e32 v81, s52, v81
	v_and_b32_e32 v85, s52, v85
	v_fma_f32 v96, v90, v80, v88
	v_fma_f32 v97, v93, v84, v89
	v_fma_f32 v96, v91, v81, v96
	v_fma_f32 v97, v94, v85, v97
	v_fma_f32 v96, v92, v82, v96
	v_fma_f32 v97, v95, v86, v97
	v_fma_f32 v100, v90, v81, v88
	v_fma_f32 v101, v93, v85, v89
	v_fma_f32 v100, v91, v82, v100
	v_fma_f32 v101, v94, v86, v101
	v_fma_f32 v100, v92, v83, v100
	v_fma_f32 v101, v95, v87, v101
	v_mul_f32_e32 v98, 0x3d372713, v96
	v_mul_f32_e32 v102, 0x3d372713, v100
	v_mul_f32_e32 v98, v96, v98
	v_mul_f32_e32 v102, v100, v102
	v_fma_f32 v98, v96, v98, v96
	v_fma_f32 v102, v100, v102, v100
	v_mul_f32_e32 v98, 0x3f4c422a, v98
	v_mul_f32_e32 v102, 0x3f4c422a, v102
	v_add_f32_e32 v98, v98, v98
	v_add_f32_e32 v102, v102, v102
	v_mul_f32_e32 v98, 0xbfb8aa3b, v98
	v_mul_f32_e32 v102, 0xbfb8aa3b, v102
	v_exp_f32_e32 v98, v98
	v_exp_f32_e32 v102, v102
	s_nop 0
	v_add_f32_e32 v98, 1.0, v98
	v_add_f32_e32 v102, 1.0, v102
	v_rcp_f32_e32 v98, v98
	v_rcp_f32_e32 v102, v102
	s_nop 0
	v_mul_f32_e32 v96, v96, v98
	v_mul_f32_e32 v100, v100, v102
	v_mul_f32_e32 v96, v96, v97
	v_mul_f32_e32 v100, v100, v101
	v_cvt_pk_bf16_f32 v96, v96, v96
	v_cvt_pk_bf16_f32 v100, v100, v100
	global_store_short v113, v96, s[28:29] offset:1024
	global_store_short v113, v100, s[30:31] offset:1024
.Lfix11_no5b:
.LBB0_1279:
	s_waitcnt lgkmcnt(0)
	s_add_u32 s33, s2, 0x1e00000
	s_addc_u32 s42, s3, 0
	s_waitcnt vmcnt(0)
	s_barrier
	s_load_dwordx8 s[16:23], s[0:1], 0xd0
	s_add_u32 s43, s2, 0x4900000
	s_addc_u32 s44, s3, 0
	s_add_u32 s4, s2, 0xc800000
	s_waitcnt vmcnt(4)
	v_mov_b32_e32 v9, v192
	s_addc_u32 s5, s3, 0
	s_and_b64 vcc, exec, s[6:7]
	v_readfirstlane_b32 s10, v9
	s_cbranch_vccnz .LBB0_1337
	s_lshr_b32 s8, s97, 29
	s_add_i32 s13, s96, s8
	s_and_b32 s8, s13, -8
	s_sub_i32 s11, s96, s8
	s_cmp_gt_i32 s11, -1
	s_cbranch_scc0 .LBB0_1282
	s_lshl_b32 s12, s11, 5
	s_ashr_i32 s13, s13, 3
	s_cbranch_execz .LBB0_1283
	s_branch .LBB0_1284
